# v66 + SSD per-chunk 64-lane prefix sum of the log-decay done with DPP row shifts/broadcasts (f32) instead of six LDS bpermute round trips
# speedup vs baseline: 1.0166x; 1.0027x over previous
; DI float bf2f(u16 b) { return __uint_as_float(((unsigned)b) << 16); }
; DI float softplus_f(float x) { return x > 20.f ? x : log1pf(__expf(x)); }
; template <int PROBE, int SONLY, int CPS>
; DI void ssd_chunk_loop(const Params& p, int layer, int b, int e, int c0, f32x4 (&h)[8], float& dtot, bool write_final) {
;     ...
;     if (w == 0) {
;       const float dtv = softplus_f(bf2f(pru) + dtb);
;       float a = dtv * ah;
; #pragma unroll
;       for (int d = 1; d < 64; d <<= 1) { const float t = __shfl_up(a, d); if (lane >= d) a += t; }
;       dt_s[lane] = dtv; acs_s[lane] = a;
;     }
.LBB0_482:
	s_or_b64 exec, exec, s[52:53]
	v_and_b32_e32 v2, 64, v190
	v_add_u32_e32 v3, -1, v190
	v_cmp_lt_i32_e64 s[0:1], v3, v2
	v_mul_f32_e64 v1, v0, -v80
	s_nop 4
	v_add_f32_dpp v3, v1, v1 row_shr:1 row_mask:0xf bank_mask:0xf bound_ctrl:1
	s_nop 1
	v_add_f32_dpp v3, v1, v3 row_shr:2 row_mask:0xf bank_mask:0xf bound_ctrl:1
	s_nop 1
	v_add_f32_dpp v3, v1, v3 row_shr:3 row_mask:0xf bank_mask:0xf bound_ctrl:1
	s_nop 1
	v_add_f32_dpp v3, v3, v3 row_shr:4 row_mask:0xf bank_mask:0xe
	s_nop 1
	v_add_f32_dpp v3, v3, v3 row_shr:8 row_mask:0xf bank_mask:0xc
	s_nop 1
	v_add_f32_dpp v3, v3, v3 row_bcast:15 row_mask:0xa bank_mask:0xf
	s_nop 1
	v_add_f32_dpp v3, v3, v3 row_bcast:31 row_mask:0xc bank_mask:0xf
	v_mov_b32_e32 v1, v3
	ds_write_b32 v69, v0
	ds_write_b32 v81, v1

; DI float bf2f(u16 b) { return __uint_as_float(((unsigned)b) << 16); }
; DI float softplus_f(float x) { return x > 20.f ? x : log1pf(__expf(x)); }
; template <int PROBE, int SONLY, int CPS>
; DI void ssd_chunk_loop(const Params& p, int layer, int b, int e, int c0, f32x4 (&h)[8], float& dtot, bool write_final) {
;     ...
;     if (w == 0) {
;       const float dtv = softplus_f(bf2f(pru) + dtb);
;       float a = dtv * ah;
; #pragma unroll
;       for (int d = 1; d < 64; d <<= 1) { const float t = __shfl_up(a, d); if (lane >= d) a += t; }
;       dt_s[lane] = dtv; acs_s[lane] = a;
;     }
.LBB0_514:
	s_or_b64 exec, exec, s[6:7]
	v_mul_f32_e64 v33, v32, -v204
	s_nop 4
	v_add_f32_dpp v34, v33, v33 row_shr:1 row_mask:0xf bank_mask:0xf bound_ctrl:1
	s_nop 1
	v_add_f32_dpp v34, v33, v34 row_shr:2 row_mask:0xf bank_mask:0xf bound_ctrl:1
	s_nop 1
	v_add_f32_dpp v34, v33, v34 row_shr:3 row_mask:0xf bank_mask:0xf bound_ctrl:1
	s_nop 1
	v_add_f32_dpp v34, v34, v34 row_shr:4 row_mask:0xf bank_mask:0xe
	s_nop 1
	v_add_f32_dpp v34, v34, v34 row_shr:8 row_mask:0xf bank_mask:0xc
	s_nop 1
	v_add_f32_dpp v34, v34, v34 row_bcast:15 row_mask:0xa bank_mask:0xf
	s_nop 1
	v_add_f32_dpp v34, v34, v34 row_bcast:31 row_mask:0xc bank_mask:0xf
	v_mov_b32_e32 v33, v34
	ds_write_b32 v215, v32
	ds_write_b32 v205, v33

; DI float bf2f(u16 b) { return __uint_as_float(((unsigned)b) << 16); }
; DI float softplus_f(float x) { return x > 20.f ? x : log1pf(__expf(x)); }
; template <int PROBE, int SONLY, int CPS>
; DI void ssd_chunk_loop(const Params& p, int layer, int b, int e, int c0, f32x4 (&h)[8], float& dtot, bool write_final) {
;     ...
;     if (w == 0) {
;       const float dtv = softplus_f(bf2f(pru) + dtb);
;       float a = dtv * ah;
; #pragma unroll
;       for (int d = 1; d < 64; d <<= 1) { const float t = __shfl_up(a, d); if (lane >= d) a += t; }
;       dt_s[lane] = dtv; acs_s[lane] = a;
;     }
.LBB0_566:
	s_or_b64 exec, exec, s[84:85]
	v_mul_f32_e64 v33, v32, -v150
	s_nop 4
	v_add_f32_dpp v34, v33, v33 row_shr:1 row_mask:0xf bank_mask:0xf bound_ctrl:1
	s_nop 1
	v_add_f32_dpp v34, v33, v34 row_shr:2 row_mask:0xf bank_mask:0xf bound_ctrl:1
	s_nop 1
	v_add_f32_dpp v34, v33, v34 row_shr:3 row_mask:0xf bank_mask:0xf bound_ctrl:1
	s_nop 1
	v_add_f32_dpp v34, v34, v34 row_shr:4 row_mask:0xf bank_mask:0xe
	s_nop 1
	v_add_f32_dpp v34, v34, v34 row_shr:8 row_mask:0xf bank_mask:0xc
	s_nop 1
	v_add_f32_dpp v34, v34, v34 row_bcast:15 row_mask:0xa bank_mask:0xf
	s_nop 1
	v_add_f32_dpp v34, v34, v34 row_bcast:31 row_mask:0xc bank_mask:0xf
	v_mov_b32_e32 v33, v34
	ds_write_b32 v165, v32
	ds_write_b32 v151, v33

; DI void xcd_barrier(const XcdBarrier& b) {
;   asm volatile("s_waitcnt vmcnt(0)" ::: "memory");
;   __syncthreads();
;   if (threadIdx.x == 0) {
;     unsigned* bar = b.bar;
;     __builtin_amdgcn_s_waitcnt(0);
;     unsigned nloc = b.st[0], nx = b.st[1];
;     if (nloc == 0u) { xcd_barrier_complete(bar, b.x, nloc, nx); b.st[0] = nloc; b.st[1] = nx; }
.LBB0_620:
	s_nop 0
	s_nop 0
	s_nop 0
	s_nop 0
	s_nop 0
	s_nop 0
	s_nop 0
	s_nop 0
	s_nop 0
	s_nop 0
	s_nop 0
	s_nop 0
	s_nop 0
	s_nop 0
	s_nop 0
	s_nop 0
	s_nop 0
	s_nop 0
	s_nop 0
	s_nop 0
	s_nop 0
	s_nop 0
	s_nop 0
	s_nop 0
	s_nop 0
	s_nop 0
	s_nop 0
	s_nop 0
	s_nop 0
	s_nop 0
	s_nop 0
	s_nop 0
	s_nop 0
	s_nop 0
	s_nop 0
	s_nop 0
	s_nop 0
	s_nop 0
	s_nop 0
	s_nop 0
	s_nop 0
	s_nop 0
	s_nop 0
	s_nop 0
	s_nop 0
	s_nop 0
	s_nop 0
	s_nop 0
	s_waitcnt vmcnt(0)
	s_barrier
	s_mov_b64 s[0:1], exec
	v_readlane_b32 s6, v252, 1
	v_readlane_b32 s7, v252, 2
	s_and_b64 s[6:7], s[0:1], s[6:7]
	s_mov_b64 exec, s[6:7]
	s_cbranch_execz .LBB0_672
	s_waitcnt vmcnt(0) expcnt(0) lgkmcnt(0)
	ds_read_b32 v2, v161
	ds_read_b32 v0, v161 offset:4
	s_waitcnt lgkmcnt(1)
	v_cmp_ne_u32_e32 vcc, 0, v2
	s_cbranch_vccnz .LBB0_636
	s_mov_b32 s2, 1
	s_branch .LBB0_624
